# all s_setprio brackets removed from the GEMM K-loops (A/B against v11 which kept one bracket per MFMA segment)
# baseline (speedup 1.0000x reference)
.Lpeel_join375_1:
	s_waitcnt lgkmcnt(0)
	s_barrier
	s_waitcnt lgkmcnt(0)
	v_mfma_f32_16x16x32_bf16 v[120:123], v[128:131], v[178:181], 0
	v_mfma_f32_16x16x32_bf16 v[124:127], v[136:139], v[178:181], 0
	v_mfma_f32_16x16x32_bf16 v[100:103], v[128:131], v[206:209], 0
	v_mfma_f32_16x16x32_bf16 v[96:99], v[136:139], v[206:209], 0
	v_mfma_f32_16x16x32_bf16 v[84:87], v[128:131], v[214:217], 0
	v_mfma_f32_16x16x32_bf16 v[80:83], v[136:139], v[214:217], 0
	v_mfma_f32_16x16x32_bf16 v[68:71], v[128:131], v[222:225], 0
	v_mfma_f32_16x16x32_bf16 v[64:67], v[136:139], v[222:225], 0
	v_mfma_f32_16x16x32_bf16 v[120:123], v[132:135], v[202:205], v[120:123]
	v_mfma_f32_16x16x32_bf16 v[124:127], v[140:143], v[202:205], v[124:127]
	v_mfma_f32_16x16x32_bf16 v[100:103], v[132:135], v[210:213], v[100:103]
	v_mfma_f32_16x16x32_bf16 v[96:99], v[140:143], v[210:213], v[96:99]
	v_mfma_f32_16x16x32_bf16 v[84:87], v[132:135], v[218:221], v[84:87]
	v_mfma_f32_16x16x32_bf16 v[80:83], v[140:143], v[218:221], v[80:83]
	v_mfma_f32_16x16x32_bf16 v[68:71], v[132:135], v[226:229], v[68:71]
	v_mfma_f32_16x16x32_bf16 v[64:67], v[140:143], v[226:229], v[64:67]
	v_mfma_f32_16x16x32_bf16 v[116:119], v[144:147], v[178:181], 0
	v_mfma_f32_16x16x32_bf16 v[112:115], v[170:173], v[178:181], 0
	v_mfma_f32_16x16x32_bf16 v[108:111], v[144:147], v[206:209], 0
	v_mfma_f32_16x16x32_bf16 v[104:107], v[170:173], v[206:209], 0
	v_mfma_f32_16x16x32_bf16 v[92:95], v[144:147], v[214:217], 0
	v_mfma_f32_16x16x32_bf16 v[88:91], v[170:173], v[214:217], 0
	v_mfma_f32_16x16x32_bf16 v[76:79], v[144:147], v[222:225], 0
	v_mfma_f32_16x16x32_bf16 v[72:75], v[170:173], v[222:225], 0
	v_mfma_f32_16x16x32_bf16 v[116:119], v[148:151], v[202:205], v[116:119]
	v_mfma_f32_16x16x32_bf16 v[112:115], v[174:177], v[202:205], v[112:115]
	v_mfma_f32_16x16x32_bf16 v[108:111], v[148:151], v[210:213], v[108:111]
	v_mfma_f32_16x16x32_bf16 v[104:107], v[174:177], v[210:213], v[104:107]
	v_mfma_f32_16x16x32_bf16 v[92:95], v[148:151], v[218:221], v[92:95]
	v_mfma_f32_16x16x32_bf16 v[88:91], v[174:177], v[218:221], v[88:91]
	v_mfma_f32_16x16x32_bf16 v[76:79], v[148:151], v[226:229], v[76:79]
	v_mfma_f32_16x16x32_bf16 v[72:75], v[174:177], v[226:229], v[72:75]
	s_barrier
	s_add_i32 s12, s12, s17
	v_lshl_add_u64 v[230:231], s[14:15], 0, v[154:155]
	s_mov_b32 m0, s12
	ds_read_b128 v[178:181], v157 offset:16384
	ds_read_b128 v[202:205], v157 offset:17408
	ds_read_b128 v[206:209], v157 offset:18432
	ds_read_b128 v[210:213], v157 offset:19456
	ds_read_b128 v[214:217], v157 offset:20480
	ds_read_b128 v[218:221], v157 offset:21504
	ds_read_b128 v[222:225], v157 offset:22528
	ds_read_b128 v[226:229], v157 offset:23552
	global_load_lds_dwordx4 v[230:231], off
	s_add_i32 m0, s12, 0x2000
	v_lshl_add_u64 v[232:233], s[14:15], 0, v[162:163]
	s_add_u32 s14, s14, s24
	s_addc_u32 s15, s15, s25
	s_add_i32 s2, s2, s17
	global_load_lds_dwordx4 v[232:233], off
	v_lshl_add_u64 v[234:235], s[14:15], 0, v[154:155]
	s_mov_b32 m0, s2
	v_lshl_add_u64 v[236:237], s[14:15], 0, v[162:163]
	global_load_lds_dwordx4 v[234:235], off
	s_add_i32 m0, s2, 0x2000
	v_lshl_add_u64 v[238:239], s[0:1], 0, v[158:159]
	global_load_lds_dwordx4 v[236:237], off
	s_mov_b32 m0, s45
	v_lshl_add_u64 v[240:241], s[0:1], 0, v[160:161]
	global_load_lds_dwordx4 v[238:239], off
	s_mov_b32 m0, s83
	s_nop 0
	global_load_lds_dwordx4 v[240:241], off
	s_lshl_b32 s99, s17, 1
	s_add_i32 m0, s99, 0x20000
	s_lshl_b32 s98, s65, 14
	s_add_i32 s98, s98, s99
	s_add_u32 s98, s100, s98
	s_addc_u32 s99, s101, 0
	global_load_lds_dwordx4 v248, s[98:99]
	global_load_lds_dwordx4 v248, s[98:99] offset:1024
	s_cmp_eq_u32 s18, 1
	s_cbranch_scc1 .Lpeel_strict375_2
	s_waitcnt vmcnt(18)
	s_branch .Lpeel_join375_2

.Lpeel_join375_2:
	s_waitcnt lgkmcnt(0)
	s_barrier
	s_waitcnt lgkmcnt(0)
	v_mfma_f32_16x16x32_bf16 v[52:55], v[128:131], v[178:181], 0
	v_mfma_f32_16x16x32_bf16 v[48:51], v[136:139], v[178:181], 0
	v_mfma_f32_16x16x32_bf16 v[36:39], v[128:131], v[206:209], 0
	v_mfma_f32_16x16x32_bf16 v[32:35], v[136:139], v[206:209], 0
	v_mfma_f32_16x16x32_bf16 v[20:23], v[128:131], v[214:217], 0
	v_mfma_f32_16x16x32_bf16 v[16:19], v[136:139], v[214:217], 0
	v_mfma_f32_16x16x32_bf16 v[4:7], v[128:131], v[222:225], 0
	v_mfma_f32_16x16x32_bf16 v[0:3], v[136:139], v[222:225], 0
	v_mfma_f32_16x16x32_bf16 v[52:55], v[132:135], v[202:205], v[52:55]
	v_mfma_f32_16x16x32_bf16 v[48:51], v[140:143], v[202:205], v[48:51]
	v_mfma_f32_16x16x32_bf16 v[36:39], v[132:135], v[210:213], v[36:39]
	v_mfma_f32_16x16x32_bf16 v[32:35], v[140:143], v[210:213], v[32:35]
	v_mfma_f32_16x16x32_bf16 v[20:23], v[132:135], v[218:221], v[20:23]
	v_mfma_f32_16x16x32_bf16 v[16:19], v[140:143], v[218:221], v[16:19]
	v_mfma_f32_16x16x32_bf16 v[4:7], v[132:135], v[226:229], v[4:7]
	v_mfma_f32_16x16x32_bf16 v[0:3], v[140:143], v[226:229], v[0:3]
	v_mfma_f32_16x16x32_bf16 v[60:63], v[144:147], v[178:181], 0
	v_mfma_f32_16x16x32_bf16 v[56:59], v[170:173], v[178:181], 0
	v_mfma_f32_16x16x32_bf16 v[44:47], v[144:147], v[206:209], 0
	v_mfma_f32_16x16x32_bf16 v[40:43], v[170:173], v[206:209], 0
	v_mfma_f32_16x16x32_bf16 v[28:31], v[144:147], v[214:217], 0
	v_mfma_f32_16x16x32_bf16 v[24:27], v[170:173], v[214:217], 0
	v_mfma_f32_16x16x32_bf16 v[12:15], v[144:147], v[222:225], 0
	v_mfma_f32_16x16x32_bf16 v[8:11], v[170:173], v[222:225], 0
	v_mfma_f32_16x16x32_bf16 v[60:63], v[148:151], v[202:205], v[60:63]
	v_mfma_f32_16x16x32_bf16 v[56:59], v[174:177], v[202:205], v[56:59]
	v_mfma_f32_16x16x32_bf16 v[44:47], v[148:151], v[210:213], v[44:47]
	v_mfma_f32_16x16x32_bf16 v[40:43], v[174:177], v[210:213], v[40:43]
	v_mfma_f32_16x16x32_bf16 v[28:31], v[148:151], v[218:221], v[28:31]
	v_mfma_f32_16x16x32_bf16 v[24:27], v[174:177], v[218:221], v[24:27]
	v_mfma_f32_16x16x32_bf16 v[12:15], v[148:151], v[226:229], v[12:15]
	v_mfma_f32_16x16x32_bf16 v[8:11], v[174:177], v[226:229], v[8:11]
	s_barrier
	s_add_i32 s2, 0, 0x18000
	s_add_i32 s12, 0, 0x1c000
	v_add_u32_e32 v140, s2, v195
	v_add_u32_e32 v174, s12, v195
	ds_read_b128 v[128:131], v140
	ds_read_b128 v[132:135], v140 offset:1024
	ds_read_b128 v[136:139], v140 offset:2048
	ds_read_b128 v[140:143], v140 offset:3072
	ds_read_b128 v[144:147], v174
	ds_read_b128 v[148:151], v174 offset:1024
	ds_read_b128 v[170:173], v174 offset:2048
	ds_read_b128 v[174:177], v174 offset:3072
	s_add_u32 s0, s0, s8
	s_addc_u32 s1, s1, s9
	s_mov_b32 m0, s28
	v_lshl_add_u64 v[242:243], s[0:1], 0, v[158:159]
	ds_read_b128 v[178:181], v157 offset:32768
	ds_read_b128 v[202:205], v157 offset:33792
	ds_read_b128 v[206:209], v157 offset:34816
	ds_read_b128 v[210:213], v157 offset:35840
	ds_read_b128 v[214:217], v157 offset:36864
	ds_read_b128 v[218:221], v157 offset:37888
	ds_read_b128 v[222:225], v157 offset:38912
	ds_read_b128 v[226:229], v157 offset:39936
	global_load_lds_dwordx4 v[242:243], off
	v_lshl_add_u64 v[242:243], s[0:1], 0, v[160:161]
	s_mov_b32 m0, s29
	s_nop 0
	global_load_lds_dwordx4 v[242:243], off
	s_waitcnt vmcnt(10)
	s_waitcnt lgkmcnt(0)
	s_barrier
	s_waitcnt lgkmcnt(0)
	v_mfma_f32_16x16x32_bf16 v[120:123], v[128:131], v[178:181], v[120:123]
	v_mfma_f32_16x16x32_bf16 v[124:127], v[136:139], v[178:181], v[124:127]
	v_mfma_f32_16x16x32_bf16 v[100:103], v[128:131], v[206:209], v[100:103]
	v_mfma_f32_16x16x32_bf16 v[96:99], v[136:139], v[206:209], v[96:99]
	v_mfma_f32_16x16x32_bf16 v[84:87], v[128:131], v[214:217], v[84:87]
	v_mfma_f32_16x16x32_bf16 v[80:83], v[136:139], v[214:217], v[80:83]
	v_mfma_f32_16x16x32_bf16 v[68:71], v[128:131], v[222:225], v[68:71]
	v_mfma_f32_16x16x32_bf16 v[64:67], v[136:139], v[222:225], v[64:67]
	v_mfma_f32_16x16x32_bf16 v[120:123], v[132:135], v[202:205], v[120:123]
	v_mfma_f32_16x16x32_bf16 v[124:127], v[140:143], v[202:205], v[124:127]
	v_mfma_f32_16x16x32_bf16 v[100:103], v[132:135], v[210:213], v[100:103]
	v_mfma_f32_16x16x32_bf16 v[96:99], v[140:143], v[210:213], v[96:99]
	v_mfma_f32_16x16x32_bf16 v[84:87], v[132:135], v[218:221], v[84:87]
	v_mfma_f32_16x16x32_bf16 v[80:83], v[140:143], v[218:221], v[80:83]
	v_mfma_f32_16x16x32_bf16 v[68:71], v[132:135], v[226:229], v[68:71]
	v_mfma_f32_16x16x32_bf16 v[64:67], v[140:143], v[226:229], v[64:67]
	v_mfma_f32_16x16x32_bf16 v[116:119], v[144:147], v[178:181], v[116:119]
	v_mfma_f32_16x16x32_bf16 v[112:115], v[170:173], v[178:181], v[112:115]
	v_mfma_f32_16x16x32_bf16 v[108:111], v[144:147], v[206:209], v[108:111]
	v_mfma_f32_16x16x32_bf16 v[104:107], v[170:173], v[206:209], v[104:107]
	v_mfma_f32_16x16x32_bf16 v[92:95], v[144:147], v[214:217], v[92:95]
	v_mfma_f32_16x16x32_bf16 v[88:91], v[170:173], v[214:217], v[88:91]
	v_mfma_f32_16x16x32_bf16 v[76:79], v[144:147], v[222:225], v[76:79]
	v_mfma_f32_16x16x32_bf16 v[72:75], v[170:173], v[222:225], v[72:75]
	v_mfma_f32_16x16x32_bf16 v[116:119], v[148:151], v[202:205], v[116:119]
	v_mfma_f32_16x16x32_bf16 v[112:115], v[174:177], v[202:205], v[112:115]
	v_mfma_f32_16x16x32_bf16 v[108:111], v[148:151], v[210:213], v[108:111]
	v_mfma_f32_16x16x32_bf16 v[104:107], v[174:177], v[210:213], v[104:107]
	v_mfma_f32_16x16x32_bf16 v[92:95], v[148:151], v[218:221], v[92:95]
	v_mfma_f32_16x16x32_bf16 v[88:91], v[174:177], v[218:221], v[88:91]
	v_mfma_f32_16x16x32_bf16 v[76:79], v[148:151], v[226:229], v[76:79]
	v_mfma_f32_16x16x32_bf16 v[72:75], v[174:177], v[226:229], v[72:75]
	s_barrier
	s_add_i32 s0, s2, s17
	v_lshl_add_u64 v[230:231], v[230:231], 0, s[36:37]
	s_mov_b32 m0, s0
	ds_read_b128 v[178:181], v157 offset:49152
	ds_read_b128 v[202:205], v157 offset:50176
	ds_read_b128 v[206:209], v157 offset:51200
	ds_read_b128 v[210:213], v157 offset:52224
	ds_read_b128 v[214:217], v157 offset:53248
	ds_read_b128 v[218:221], v157 offset:54272
	ds_read_b128 v[222:225], v157 offset:55296
	ds_read_b128 v[226:229], v157 offset:56320
	global_load_lds_dwordx4 v[230:231], off
	v_lshl_add_u64 v[230:231], v[232:233], 0, s[36:37]
	s_add_i32 m0, s0, 0x2000
	s_add_i32 s0, s12, s17
	global_load_lds_dwordx4 v[230:231], off
	v_lshl_add_u64 v[230:231], v[234:235], 0, s[36:37]
	s_mov_b32 m0, s0
	s_nop 0
	global_load_lds_dwordx4 v[230:231], off
	v_lshl_add_u64 v[230:231], v[236:237], 0, s[36:37]
	s_add_i32 m0, s0, 0x2000
	s_nop 0
	global_load_lds_dwordx4 v[230:231], off
	v_lshl_add_u64 v[230:231], v[238:239], 0, s[36:37]
	s_mov_b32 m0, s10
	s_nop 0
	global_load_lds_dwordx4 v[230:231], off
	v_lshl_add_u64 v[230:231], v[240:241], 0, s[36:37]
	s_mov_b32 m0, s11
	s_nop 0
	global_load_lds_dwordx4 v[230:231], off
	s_waitcnt vmcnt(10)
	s_waitcnt lgkmcnt(0)
	s_barrier
	s_waitcnt lgkmcnt(0)
	v_mfma_f32_16x16x32_bf16 v[52:55], v[128:131], v[178:181], v[52:55]
	v_mfma_f32_16x16x32_bf16 v[48:51], v[136:139], v[178:181], v[48:51]
	v_mfma_f32_16x16x32_bf16 v[36:39], v[128:131], v[206:209], v[36:39]
	v_mfma_f32_16x16x32_bf16 v[32:35], v[136:139], v[206:209], v[32:35]
	v_mfma_f32_16x16x32_bf16 v[20:23], v[128:131], v[214:217], v[20:23]
	v_mfma_f32_16x16x32_bf16 v[16:19], v[136:139], v[214:217], v[16:19]
	v_mfma_f32_16x16x32_bf16 v[4:7], v[128:131], v[222:225], v[4:7]
	v_mfma_f32_16x16x32_bf16 v[0:3], v[136:139], v[222:225], v[0:3]
	v_mfma_f32_16x16x32_bf16 v[52:55], v[132:135], v[202:205], v[52:55]
	v_mfma_f32_16x16x32_bf16 v[48:51], v[140:143], v[202:205], v[48:51]
	v_mfma_f32_16x16x32_bf16 v[36:39], v[132:135], v[210:213], v[36:39]
	v_mfma_f32_16x16x32_bf16 v[32:35], v[140:143], v[210:213], v[32:35]
	v_mfma_f32_16x16x32_bf16 v[20:23], v[132:135], v[218:221], v[20:23]
	v_mfma_f32_16x16x32_bf16 v[16:19], v[140:143], v[218:221], v[16:19]
	v_mfma_f32_16x16x32_bf16 v[4:7], v[132:135], v[226:229], v[4:7]
	v_mfma_f32_16x16x32_bf16 v[0:3], v[140:143], v[226:229], v[0:3]
	v_mfma_f32_16x16x32_bf16 v[60:63], v[144:147], v[178:181], v[60:63]
	v_mfma_f32_16x16x32_bf16 v[56:59], v[170:173], v[178:181], v[56:59]
	v_mfma_f32_16x16x32_bf16 v[44:47], v[144:147], v[206:209], v[44:47]
	v_mfma_f32_16x16x32_bf16 v[40:43], v[170:173], v[206:209], v[40:43]
	v_mfma_f32_16x16x32_bf16 v[28:31], v[144:147], v[214:217], v[28:31]
	v_mfma_f32_16x16x32_bf16 v[24:27], v[170:173], v[214:217], v[24:27]
	v_mfma_f32_16x16x32_bf16 v[12:15], v[144:147], v[222:225], v[12:15]
	v_mfma_f32_16x16x32_bf16 v[8:11], v[170:173], v[222:225], v[8:11]
	v_mfma_f32_16x16x32_bf16 v[60:63], v[148:151], v[202:205], v[60:63]
	v_mfma_f32_16x16x32_bf16 v[56:59], v[174:177], v[202:205], v[56:59]
	v_mfma_f32_16x16x32_bf16 v[44:47], v[148:151], v[210:213], v[44:47]
	v_mfma_f32_16x16x32_bf16 v[40:43], v[174:177], v[210:213], v[40:43]
	v_mfma_f32_16x16x32_bf16 v[28:31], v[148:151], v[218:221], v[28:31]
	v_mfma_f32_16x16x32_bf16 v[24:27], v[174:177], v[218:221], v[24:27]
	v_mfma_f32_16x16x32_bf16 v[12:15], v[148:151], v[226:229], v[12:15]
	v_mfma_f32_16x16x32_bf16 v[8:11], v[174:177], v[226:229], v[8:11]
	s_barrier
	s_add_u32 s42, s42, 0x100
	s_addc_u32 s43, s43, 0
	s_add_u32 s46, s46, 0x100
	s_addc_u32 s47, s47, 0
	s_cmp_ge_u32 s97, s31
	s_mov_b32 s0, s97
.LBB0_375:
	s_add_i32 s97, s0, 2
	s_add_u32 s2, s42, 0x80
	s_addc_u32 s1, s43, 0
	s_add_i32 s12, 0, 0x10000
	s_cmp_eq_u32 s13, s0
	s_cselect_b32 s1, s95, s1
	s_cselect_b32 s0, s94, s2
	s_cselect_b32 s15, s55, s47
	s_cselect_b32 s14, s54, s46
	s_add_i32 s2, 0, 0x14000
	v_add_u32_e32 v140, s12, v195
	v_add_u32_e32 v174, s2, v195
	ds_read_b128 v[128:131], v140
	ds_read_b128 v[132:135], v140 offset:1024
	ds_read_b128 v[136:139], v140 offset:2048
	ds_read_b128 v[140:143], v140 offset:3072
	ds_read_b128 v[144:147], v174
	ds_read_b128 v[148:151], v174 offset:1024
	ds_read_b128 v[170:173], v174 offset:2048
	ds_read_b128 v[174:177], v174 offset:3072
	v_lshl_add_u64 v[230:231], s[42:43], 0, v[166:167]
	s_add_i32 m0, s45, 0xc000
	ds_read_b128 v[178:181], v157
	ds_read_b128 v[202:205], v157 offset:1024
	ds_read_b128 v[206:209], v157 offset:2048
	ds_read_b128 v[210:213], v157 offset:3072
	ds_read_b128 v[214:217], v157 offset:4096
	ds_read_b128 v[218:221], v157 offset:5120
	ds_read_b128 v[222:225], v157 offset:6144
	ds_read_b128 v[226:229], v157 offset:7168
	global_load_lds_dwordx4 v[230:231], off
	v_lshl_add_u64 v[230:231], s[42:43], 0, v[168:169]
	s_add_i32 m0, s45, 0xe000
	s_nop 0
	global_load_lds_dwordx4 v[230:231], off
	s_waitcnt vmcnt(8)
	s_waitcnt lgkmcnt(0)
	s_barrier
	s_waitcnt lgkmcnt(0)
	v_mfma_f32_16x16x32_bf16 v[120:123], v[128:131], v[178:181], v[120:123]
	v_mfma_f32_16x16x32_bf16 v[124:127], v[136:139], v[178:181], v[124:127]
	v_mfma_f32_16x16x32_bf16 v[100:103], v[128:131], v[206:209], v[100:103]
	v_mfma_f32_16x16x32_bf16 v[96:99], v[136:139], v[206:209], v[96:99]
	v_mfma_f32_16x16x32_bf16 v[84:87], v[128:131], v[214:217], v[84:87]
	v_mfma_f32_16x16x32_bf16 v[80:83], v[136:139], v[214:217], v[80:83]
	v_mfma_f32_16x16x32_bf16 v[68:71], v[128:131], v[222:225], v[68:71]
	v_mfma_f32_16x16x32_bf16 v[64:67], v[136:139], v[222:225], v[64:67]
	v_mfma_f32_16x16x32_bf16 v[120:123], v[132:135], v[202:205], v[120:123]
	v_mfma_f32_16x16x32_bf16 v[124:127], v[140:143], v[202:205], v[124:127]
	v_mfma_f32_16x16x32_bf16 v[100:103], v[132:135], v[210:213], v[100:103]
	v_mfma_f32_16x16x32_bf16 v[96:99], v[140:143], v[210:213], v[96:99]
	v_mfma_f32_16x16x32_bf16 v[84:87], v[132:135], v[218:221], v[84:87]
	v_mfma_f32_16x16x32_bf16 v[80:83], v[140:143], v[218:221], v[80:83]
	v_mfma_f32_16x16x32_bf16 v[68:71], v[132:135], v[226:229], v[68:71]
	v_mfma_f32_16x16x32_bf16 v[64:67], v[140:143], v[226:229], v[64:67]
	v_mfma_f32_16x16x32_bf16 v[116:119], v[144:147], v[178:181], v[116:119]
	v_mfma_f32_16x16x32_bf16 v[112:115], v[170:173], v[178:181], v[112:115]
	v_mfma_f32_16x16x32_bf16 v[108:111], v[144:147], v[206:209], v[108:111]
	v_mfma_f32_16x16x32_bf16 v[104:107], v[170:173], v[206:209], v[104:107]
	v_mfma_f32_16x16x32_bf16 v[92:95], v[144:147], v[214:217], v[92:95]
	v_mfma_f32_16x16x32_bf16 v[88:91], v[170:173], v[214:217], v[88:91]
	v_mfma_f32_16x16x32_bf16 v[76:79], v[144:147], v[222:225], v[76:79]
	v_mfma_f32_16x16x32_bf16 v[72:75], v[170:173], v[222:225], v[72:75]
	v_mfma_f32_16x16x32_bf16 v[116:119], v[148:151], v[202:205], v[116:119]
	v_mfma_f32_16x16x32_bf16 v[112:115], v[174:177], v[202:205], v[112:115]
	v_mfma_f32_16x16x32_bf16 v[108:111], v[148:151], v[210:213], v[108:111]
	v_mfma_f32_16x16x32_bf16 v[104:107], v[174:177], v[210:213], v[104:107]
	v_mfma_f32_16x16x32_bf16 v[92:95], v[148:151], v[218:221], v[92:95]
	v_mfma_f32_16x16x32_bf16 v[88:91], v[174:177], v[218:221], v[88:91]
	v_mfma_f32_16x16x32_bf16 v[76:79], v[148:151], v[226:229], v[76:79]
	v_mfma_f32_16x16x32_bf16 v[72:75], v[174:177], v[226:229], v[72:75]
	s_barrier
	s_add_i32 s12, s12, s17
	v_lshl_add_u64 v[230:231], s[14:15], 0, v[154:155]
	s_mov_b32 m0, s12
	ds_read_b128 v[178:181], v157 offset:16384
	ds_read_b128 v[202:205], v157 offset:17408
	ds_read_b128 v[206:209], v157 offset:18432
	ds_read_b128 v[210:213], v157 offset:19456
	ds_read_b128 v[214:217], v157 offset:20480
	ds_read_b128 v[218:221], v157 offset:21504
	ds_read_b128 v[222:225], v157 offset:22528
	ds_read_b128 v[226:229], v157 offset:23552
	global_load_lds_dwordx4 v[230:231], off
	s_add_i32 m0, s12, 0x2000
	v_lshl_add_u64 v[232:233], s[14:15], 0, v[162:163]
	s_add_u32 s14, s14, s24
	s_addc_u32 s15, s15, s25
	s_add_i32 s2, s2, s17
	global_load_lds_dwordx4 v[232:233], off
	v_lshl_add_u64 v[234:235], s[14:15], 0, v[154:155]
	s_mov_b32 m0, s2
	v_lshl_add_u64 v[236:237], s[14:15], 0, v[162:163]
	global_load_lds_dwordx4 v[234:235], off
	s_add_i32 m0, s2, 0x2000
	v_lshl_add_u64 v[238:239], s[0:1], 0, v[158:159]
	global_load_lds_dwordx4 v[236:237], off
	s_mov_b32 m0, s45
	v_lshl_add_u64 v[240:241], s[0:1], 0, v[160:161]
	global_load_lds_dwordx4 v[238:239], off
	s_mov_b32 m0, s83
	s_nop 0
	global_load_lds_dwordx4 v[240:241], off
	s_waitcnt vmcnt(8)
	s_waitcnt lgkmcnt(0)
	s_barrier
	s_waitcnt lgkmcnt(0)
	v_mfma_f32_16x16x32_bf16 v[52:55], v[128:131], v[178:181], v[52:55]
	v_mfma_f32_16x16x32_bf16 v[48:51], v[136:139], v[178:181], v[48:51]
	v_mfma_f32_16x16x32_bf16 v[36:39], v[128:131], v[206:209], v[36:39]
	v_mfma_f32_16x16x32_bf16 v[32:35], v[136:139], v[206:209], v[32:35]
	v_mfma_f32_16x16x32_bf16 v[20:23], v[128:131], v[214:217], v[20:23]
	v_mfma_f32_16x16x32_bf16 v[16:19], v[136:139], v[214:217], v[16:19]
	v_mfma_f32_16x16x32_bf16 v[4:7], v[128:131], v[222:225], v[4:7]
	v_mfma_f32_16x16x32_bf16 v[0:3], v[136:139], v[222:225], v[0:3]
	v_mfma_f32_16x16x32_bf16 v[52:55], v[132:135], v[202:205], v[52:55]
	v_mfma_f32_16x16x32_bf16 v[48:51], v[140:143], v[202:205], v[48:51]
	v_mfma_f32_16x16x32_bf16 v[36:39], v[132:135], v[210:213], v[36:39]
	v_mfma_f32_16x16x32_bf16 v[32:35], v[140:143], v[210:213], v[32:35]
	v_mfma_f32_16x16x32_bf16 v[20:23], v[132:135], v[218:221], v[20:23]
	v_mfma_f32_16x16x32_bf16 v[16:19], v[140:143], v[218:221], v[16:19]
	v_mfma_f32_16x16x32_bf16 v[4:7], v[132:135], v[226:229], v[4:7]
	v_mfma_f32_16x16x32_bf16 v[0:3], v[140:143], v[226:229], v[0:3]
	v_mfma_f32_16x16x32_bf16 v[60:63], v[144:147], v[178:181], v[60:63]
	v_mfma_f32_16x16x32_bf16 v[56:59], v[170:173], v[178:181], v[56:59]
	v_mfma_f32_16x16x32_bf16 v[44:47], v[144:147], v[206:209], v[44:47]
	v_mfma_f32_16x16x32_bf16 v[40:43], v[170:173], v[206:209], v[40:43]
	v_mfma_f32_16x16x32_bf16 v[28:31], v[144:147], v[214:217], v[28:31]
	v_mfma_f32_16x16x32_bf16 v[24:27], v[170:173], v[214:217], v[24:27]
	v_mfma_f32_16x16x32_bf16 v[12:15], v[144:147], v[222:225], v[12:15]
	v_mfma_f32_16x16x32_bf16 v[8:11], v[170:173], v[222:225], v[8:11]
	v_mfma_f32_16x16x32_bf16 v[60:63], v[148:151], v[202:205], v[60:63]
	v_mfma_f32_16x16x32_bf16 v[56:59], v[174:177], v[202:205], v[56:59]
	v_mfma_f32_16x16x32_bf16 v[44:47], v[148:151], v[210:213], v[44:47]
	v_mfma_f32_16x16x32_bf16 v[40:43], v[174:177], v[210:213], v[40:43]
	v_mfma_f32_16x16x32_bf16 v[28:31], v[148:151], v[218:221], v[28:31]
	v_mfma_f32_16x16x32_bf16 v[24:27], v[174:177], v[218:221], v[24:27]
	v_mfma_f32_16x16x32_bf16 v[12:15], v[148:151], v[226:229], v[12:15]
	v_mfma_f32_16x16x32_bf16 v[8:11], v[174:177], v[226:229], v[8:11]
	s_barrier
	s_add_i32 s2, 0, 0x18000
	s_add_i32 s12, 0, 0x1c000
	v_add_u32_e32 v140, s2, v195
	v_add_u32_e32 v174, s12, v195
	ds_read_b128 v[128:131], v140
	ds_read_b128 v[132:135], v140 offset:1024
	ds_read_b128 v[136:139], v140 offset:2048
	ds_read_b128 v[140:143], v140 offset:3072
	ds_read_b128 v[144:147], v174
	ds_read_b128 v[148:151], v174 offset:1024
	ds_read_b128 v[170:173], v174 offset:2048
	ds_read_b128 v[174:177], v174 offset:3072
	s_add_u32 s0, s0, s8
	s_addc_u32 s1, s1, s9
	s_mov_b32 m0, s28
	v_lshl_add_u64 v[242:243], s[0:1], 0, v[158:159]
	ds_read_b128 v[178:181], v157 offset:32768
	ds_read_b128 v[202:205], v157 offset:33792
	ds_read_b128 v[206:209], v157 offset:34816
	ds_read_b128 v[210:213], v157 offset:35840
	ds_read_b128 v[214:217], v157 offset:36864
	ds_read_b128 v[218:221], v157 offset:37888
	ds_read_b128 v[222:225], v157 offset:38912
	ds_read_b128 v[226:229], v157 offset:39936
	global_load_lds_dwordx4 v[242:243], off
	v_lshl_add_u64 v[242:243], s[0:1], 0, v[160:161]
	s_mov_b32 m0, s29
	s_nop 0
	global_load_lds_dwordx4 v[242:243], off
	s_waitcnt vmcnt(8)
	s_waitcnt lgkmcnt(0)
	s_barrier
	s_waitcnt lgkmcnt(0)
	v_mfma_f32_16x16x32_bf16 v[120:123], v[128:131], v[178:181], v[120:123]
	v_mfma_f32_16x16x32_bf16 v[124:127], v[136:139], v[178:181], v[124:127]
	v_mfma_f32_16x16x32_bf16 v[100:103], v[128:131], v[206:209], v[100:103]
	v_mfma_f32_16x16x32_bf16 v[96:99], v[136:139], v[206:209], v[96:99]
	v_mfma_f32_16x16x32_bf16 v[84:87], v[128:131], v[214:217], v[84:87]
	v_mfma_f32_16x16x32_bf16 v[80:83], v[136:139], v[214:217], v[80:83]
	v_mfma_f32_16x16x32_bf16 v[68:71], v[128:131], v[222:225], v[68:71]
	v_mfma_f32_16x16x32_bf16 v[64:67], v[136:139], v[222:225], v[64:67]
	v_mfma_f32_16x16x32_bf16 v[120:123], v[132:135], v[202:205], v[120:123]
	v_mfma_f32_16x16x32_bf16 v[124:127], v[140:143], v[202:205], v[124:127]
	v_mfma_f32_16x16x32_bf16 v[100:103], v[132:135], v[210:213], v[100:103]
	v_mfma_f32_16x16x32_bf16 v[96:99], v[140:143], v[210:213], v[96:99]
	v_mfma_f32_16x16x32_bf16 v[84:87], v[132:135], v[218:221], v[84:87]
	v_mfma_f32_16x16x32_bf16 v[80:83], v[140:143], v[218:221], v[80:83]
	v_mfma_f32_16x16x32_bf16 v[68:71], v[132:135], v[226:229], v[68:71]
	v_mfma_f32_16x16x32_bf16 v[64:67], v[140:143], v[226:229], v[64:67]
	v_mfma_f32_16x16x32_bf16 v[116:119], v[144:147], v[178:181], v[116:119]
	v_mfma_f32_16x16x32_bf16 v[112:115], v[170:173], v[178:181], v[112:115]
	v_mfma_f32_16x16x32_bf16 v[108:111], v[144:147], v[206:209], v[108:111]
	v_mfma_f32_16x16x32_bf16 v[104:107], v[170:173], v[206:209], v[104:107]
	v_mfma_f32_16x16x32_bf16 v[92:95], v[144:147], v[214:217], v[92:95]
	v_mfma_f32_16x16x32_bf16 v[88:91], v[170:173], v[214:217], v[88:91]
	v_mfma_f32_16x16x32_bf16 v[76:79], v[144:147], v[222:225], v[76:79]
	v_mfma_f32_16x16x32_bf16 v[72:75], v[170:173], v[222:225], v[72:75]
	v_mfma_f32_16x16x32_bf16 v[116:119], v[148:151], v[202:205], v[116:119]
	v_mfma_f32_16x16x32_bf16 v[112:115], v[174:177], v[202:205], v[112:115]
	v_mfma_f32_16x16x32_bf16 v[108:111], v[148:151], v[210:213], v[108:111]
	v_mfma_f32_16x16x32_bf16 v[104:107], v[174:177], v[210:213], v[104:107]
	v_mfma_f32_16x16x32_bf16 v[92:95], v[148:151], v[218:221], v[92:95]
	v_mfma_f32_16x16x32_bf16 v[88:91], v[174:177], v[218:221], v[88:91]
	v_mfma_f32_16x16x32_bf16 v[76:79], v[148:151], v[226:229], v[76:79]
	v_mfma_f32_16x16x32_bf16 v[72:75], v[174:177], v[226:229], v[72:75]
	s_barrier
	s_add_i32 s0, s2, s17
	v_lshl_add_u64 v[230:231], v[230:231], 0, s[36:37]
	s_mov_b32 m0, s0
	ds_read_b128 v[178:181], v157 offset:49152
	ds_read_b128 v[202:205], v157 offset:50176
	ds_read_b128 v[206:209], v157 offset:51200
	ds_read_b128 v[210:213], v157 offset:52224
	ds_read_b128 v[214:217], v157 offset:53248
	ds_read_b128 v[218:221], v157 offset:54272
	ds_read_b128 v[222:225], v157 offset:55296
	ds_read_b128 v[226:229], v157 offset:56320
	global_load_lds_dwordx4 v[230:231], off
	v_lshl_add_u64 v[230:231], v[232:233], 0, s[36:37]
	s_add_i32 m0, s0, 0x2000
	s_add_i32 s0, s12, s17
	global_load_lds_dwordx4 v[230:231], off
	v_lshl_add_u64 v[230:231], v[234:235], 0, s[36:37]
	s_mov_b32 m0, s0
	s_nop 0
	global_load_lds_dwordx4 v[230:231], off
	v_lshl_add_u64 v[230:231], v[236:237], 0, s[36:37]
	s_add_i32 m0, s0, 0x2000
	s_nop 0
	global_load_lds_dwordx4 v[230:231], off
	v_lshl_add_u64 v[230:231], v[238:239], 0, s[36:37]
	s_mov_b32 m0, s10
	s_nop 0
	global_load_lds_dwordx4 v[230:231], off
	v_lshl_add_u64 v[230:231], v[240:241], 0, s[36:37]
	s_mov_b32 m0, s11
	s_nop 0
	global_load_lds_dwordx4 v[230:231], off
	s_waitcnt vmcnt(8)
	s_waitcnt lgkmcnt(0)
	s_barrier
	s_waitcnt lgkmcnt(0)
	v_mfma_f32_16x16x32_bf16 v[52:55], v[128:131], v[178:181], v[52:55]
	v_mfma_f32_16x16x32_bf16 v[48:51], v[136:139], v[178:181], v[48:51]
	v_mfma_f32_16x16x32_bf16 v[36:39], v[128:131], v[206:209], v[36:39]
	v_mfma_f32_16x16x32_bf16 v[32:35], v[136:139], v[206:209], v[32:35]
	v_mfma_f32_16x16x32_bf16 v[20:23], v[128:131], v[214:217], v[20:23]
	v_mfma_f32_16x16x32_bf16 v[16:19], v[136:139], v[214:217], v[16:19]
	v_mfma_f32_16x16x32_bf16 v[4:7], v[128:131], v[222:225], v[4:7]
	v_mfma_f32_16x16x32_bf16 v[0:3], v[136:139], v[222:225], v[0:3]
	v_mfma_f32_16x16x32_bf16 v[52:55], v[132:135], v[202:205], v[52:55]
	v_mfma_f32_16x16x32_bf16 v[48:51], v[140:143], v[202:205], v[48:51]
	v_mfma_f32_16x16x32_bf16 v[36:39], v[132:135], v[210:213], v[36:39]
	v_mfma_f32_16x16x32_bf16 v[32:35], v[140:143], v[210:213], v[32:35]
	v_mfma_f32_16x16x32_bf16 v[20:23], v[132:135], v[218:221], v[20:23]
	v_mfma_f32_16x16x32_bf16 v[16:19], v[140:143], v[218:221], v[16:19]
	v_mfma_f32_16x16x32_bf16 v[4:7], v[132:135], v[226:229], v[4:7]
	v_mfma_f32_16x16x32_bf16 v[0:3], v[140:143], v[226:229], v[0:3]
	v_mfma_f32_16x16x32_bf16 v[60:63], v[144:147], v[178:181], v[60:63]
	v_mfma_f32_16x16x32_bf16 v[56:59], v[170:173], v[178:181], v[56:59]
	v_mfma_f32_16x16x32_bf16 v[44:47], v[144:147], v[206:209], v[44:47]
	v_mfma_f32_16x16x32_bf16 v[40:43], v[170:173], v[206:209], v[40:43]
	v_mfma_f32_16x16x32_bf16 v[28:31], v[144:147], v[214:217], v[28:31]
	v_mfma_f32_16x16x32_bf16 v[24:27], v[170:173], v[214:217], v[24:27]
	v_mfma_f32_16x16x32_bf16 v[12:15], v[144:147], v[222:225], v[12:15]
	v_mfma_f32_16x16x32_bf16 v[8:11], v[170:173], v[222:225], v[8:11]
	v_mfma_f32_16x16x32_bf16 v[60:63], v[148:151], v[202:205], v[60:63]
	v_mfma_f32_16x16x32_bf16 v[56:59], v[174:177], v[202:205], v[56:59]
	v_mfma_f32_16x16x32_bf16 v[44:47], v[148:151], v[210:213], v[44:47]
	v_mfma_f32_16x16x32_bf16 v[40:43], v[174:177], v[210:213], v[40:43]
	v_mfma_f32_16x16x32_bf16 v[28:31], v[148:151], v[218:221], v[28:31]
	v_mfma_f32_16x16x32_bf16 v[24:27], v[174:177], v[218:221], v[24:27]
	v_mfma_f32_16x16x32_bf16 v[12:15], v[148:151], v[226:229], v[12:15]
	v_mfma_f32_16x16x32_bf16 v[8:11], v[174:177], v[226:229], v[8:11]
	s_barrier
	s_add_u32 s42, s42, 0x100
	s_addc_u32 s43, s43, 0
	s_add_u32 s46, s46, 0x100
	s_addc_u32 s47, s47, 0
	s_cmp_ge_u32 s97, s31
	s_mov_b32 s0, s97
	s_cbranch_scc0 .LBB0_375
	s_and_b64 vcc, exec, s[74:75]
	s_cbranch_vccz .LBB0_378
	s_barrier

.Lpeel_join482_1:
	s_waitcnt lgkmcnt(0)
	s_barrier
	s_waitcnt lgkmcnt(0)
	v_mfma_f32_16x16x32_bf16 v[124:127], v[128:131], v[202:205], 0
	v_mfma_f32_16x16x32_bf16 v[120:123], v[146:149], v[202:205], 0
	v_mfma_f32_16x16x32_bf16 v[108:111], v[128:131], v[210:213], 0
	v_mfma_f32_16x16x32_bf16 v[104:107], v[146:149], v[210:213], 0
	v_mfma_f32_16x16x32_bf16 v[92:95], v[128:131], v[218:221], 0
	v_mfma_f32_16x16x32_bf16 v[88:91], v[146:149], v[218:221], 0
	v_mfma_f32_16x16x32_bf16 v[76:79], v[128:131], v[226:229], 0
	v_mfma_f32_16x16x32_bf16 v[72:75], v[146:149], v[226:229], 0
	v_mfma_f32_16x16x32_bf16 v[124:127], v[132:135], v[206:209], v[124:127]
	v_mfma_f32_16x16x32_bf16 v[120:123], v[158:161], v[206:209], v[120:123]
	v_mfma_f32_16x16x32_bf16 v[108:111], v[132:135], v[214:217], v[108:111]
	v_mfma_f32_16x16x32_bf16 v[104:107], v[158:161], v[214:217], v[104:107]
	v_mfma_f32_16x16x32_bf16 v[92:95], v[132:135], v[222:225], v[92:95]
	v_mfma_f32_16x16x32_bf16 v[88:91], v[158:161], v[222:225], v[88:91]
	v_mfma_f32_16x16x32_bf16 v[76:79], v[132:135], v[230:233], v[76:79]
	v_mfma_f32_16x16x32_bf16 v[72:75], v[158:161], v[230:233], v[72:75]
	v_mfma_f32_16x16x32_bf16 v[116:119], v[168:171], v[202:205], 0
	v_mfma_f32_16x16x32_bf16 v[112:115], v[176:179], v[202:205], 0
	v_mfma_f32_16x16x32_bf16 v[100:103], v[168:171], v[210:213], 0
	v_mfma_f32_16x16x32_bf16 v[96:99], v[176:179], v[210:213], 0
	v_mfma_f32_16x16x32_bf16 v[84:87], v[168:171], v[218:221], 0
	v_mfma_f32_16x16x32_bf16 v[80:83], v[176:179], v[218:221], 0
	v_mfma_f32_16x16x32_bf16 v[68:71], v[168:171], v[226:229], 0
	v_mfma_f32_16x16x32_bf16 v[64:67], v[176:179], v[226:229], 0
	v_mfma_f32_16x16x32_bf16 v[116:119], v[172:175], v[206:209], v[116:119]
	v_mfma_f32_16x16x32_bf16 v[112:115], v[194:197], v[206:209], v[112:115]
	v_mfma_f32_16x16x32_bf16 v[100:103], v[172:175], v[214:217], v[100:103]
	v_mfma_f32_16x16x32_bf16 v[96:99], v[194:197], v[214:217], v[96:99]
	v_mfma_f32_16x16x32_bf16 v[84:87], v[172:175], v[222:225], v[84:87]
	v_mfma_f32_16x16x32_bf16 v[80:83], v[194:197], v[222:225], v[80:83]
	v_mfma_f32_16x16x32_bf16 v[68:71], v[172:175], v[230:233], v[68:71]
	v_mfma_f32_16x16x32_bf16 v[64:67], v[194:197], v[230:233], v[64:67]
	s_barrier
	s_add_i32 s15, s15, s2
	v_lshl_add_u64 v[150:151], s[82:83], 0, v[154:155]
	s_mov_b32 m0, s15
	ds_read_b128 v[202:205], v167 offset:16384
	ds_read_b128 v[206:209], v167 offset:17408
	ds_read_b128 v[210:213], v167 offset:18432
	ds_read_b128 v[214:217], v167 offset:19456
	ds_read_b128 v[218:221], v167 offset:20480
	ds_read_b128 v[222:225], v167 offset:21504
	ds_read_b128 v[226:229], v167 offset:22528
	ds_read_b128 v[230:233], v167 offset:23552
	global_load_lds_dwordx4 v[150:151], off
	s_add_i32 m0, s15, 0x2000
	v_lshl_add_u64 v[162:163], s[82:83], 0, v[140:141]
	s_add_u32 s82, s82, s24
	s_addc_u32 s83, s83, s25
	s_add_i32 s14, s14, s2
	global_load_lds_dwordx4 v[162:163], off
	v_lshl_add_u64 v[180:181], s[82:83], 0, v[154:155]
	s_mov_b32 m0, s14
	v_lshl_add_u64 v[234:235], s[82:83], 0, v[140:141]
	global_load_lds_dwordx4 v[180:181], off
	s_add_i32 m0, s14, 0x2000
	v_lshl_add_u64 v[236:237], s[0:1], 0, v[136:137]
	global_load_lds_dwordx4 v[234:235], off
	s_mov_b32 m0, s3
	v_lshl_add_u64 v[238:239], s[0:1], 0, v[138:139]
	global_load_lds_dwordx4 v[236:237], off
	s_mov_b32 m0, s10
	s_nop 0
	global_load_lds_dwordx4 v[238:239], off
	s_cmp_eq_u32 s92, 1
	s_cbranch_scc1 .Lpeel_strict482_2
	s_waitcnt vmcnt(24)
	s_branch .Lpeel_join482_2

.Lpeel_join482_2:
	s_waitcnt lgkmcnt(0)
	s_barrier
	s_waitcnt lgkmcnt(0)
	v_mfma_f32_16x16x32_bf16 v[60:63], v[128:131], v[202:205], 0
	v_mfma_f32_16x16x32_bf16 v[56:59], v[146:149], v[202:205], 0
	v_mfma_f32_16x16x32_bf16 v[44:47], v[128:131], v[210:213], 0
	v_mfma_f32_16x16x32_bf16 v[40:43], v[146:149], v[210:213], 0
	v_mfma_f32_16x16x32_bf16 v[28:31], v[128:131], v[218:221], 0
	v_mfma_f32_16x16x32_bf16 v[24:27], v[146:149], v[218:221], 0
	v_mfma_f32_16x16x32_bf16 v[12:15], v[128:131], v[226:229], 0
	v_mfma_f32_16x16x32_bf16 v[8:11], v[146:149], v[226:229], 0
	v_mfma_f32_16x16x32_bf16 v[60:63], v[132:135], v[206:209], v[60:63]
	v_mfma_f32_16x16x32_bf16 v[56:59], v[158:161], v[206:209], v[56:59]
	v_mfma_f32_16x16x32_bf16 v[44:47], v[132:135], v[214:217], v[44:47]
	v_mfma_f32_16x16x32_bf16 v[40:43], v[158:161], v[214:217], v[40:43]
	v_mfma_f32_16x16x32_bf16 v[28:31], v[132:135], v[222:225], v[28:31]
	v_mfma_f32_16x16x32_bf16 v[24:27], v[158:161], v[222:225], v[24:27]
	v_mfma_f32_16x16x32_bf16 v[12:15], v[132:135], v[230:233], v[12:15]
	v_mfma_f32_16x16x32_bf16 v[8:11], v[158:161], v[230:233], v[8:11]
	v_mfma_f32_16x16x32_bf16 v[52:55], v[168:171], v[202:205], 0
	v_mfma_f32_16x16x32_bf16 v[48:51], v[176:179], v[202:205], 0
	v_mfma_f32_16x16x32_bf16 v[36:39], v[168:171], v[210:213], 0
	v_mfma_f32_16x16x32_bf16 v[32:35], v[176:179], v[210:213], 0
	v_mfma_f32_16x16x32_bf16 v[20:23], v[168:171], v[218:221], 0
	v_mfma_f32_16x16x32_bf16 v[16:19], v[176:179], v[218:221], 0
	v_mfma_f32_16x16x32_bf16 v[4:7], v[168:171], v[226:229], 0
	v_mfma_f32_16x16x32_bf16 v[0:3], v[176:179], v[226:229], 0
	v_mfma_f32_16x16x32_bf16 v[52:55], v[172:175], v[206:209], v[52:55]
	v_mfma_f32_16x16x32_bf16 v[48:51], v[194:197], v[206:209], v[48:51]
	v_mfma_f32_16x16x32_bf16 v[36:39], v[172:175], v[214:217], v[36:39]
	v_mfma_f32_16x16x32_bf16 v[32:35], v[194:197], v[214:217], v[32:35]
	v_mfma_f32_16x16x32_bf16 v[20:23], v[172:175], v[222:225], v[20:23]
	v_mfma_f32_16x16x32_bf16 v[16:19], v[194:197], v[222:225], v[16:19]
	v_mfma_f32_16x16x32_bf16 v[4:7], v[172:175], v[230:233], v[4:7]
	v_mfma_f32_16x16x32_bf16 v[0:3], v[194:197], v[230:233], v[0:3]
	s_barrier
	s_add_i32 s14, 0, 0x18000
	s_add_i32 s15, 0, 0x1c000
	v_add_u32_e32 v158, s14, v165
	v_add_u32_e32 v193, s15, v165
	ds_read_b128 v[128:131], v158
	ds_read_b128 v[132:135], v158 offset:1024
	ds_read_b128 v[146:149], v158 offset:2048
	ds_read_b128 v[158:161], v158 offset:3072
	ds_read_b128 v[168:171], v193
	ds_read_b128 v[172:175], v193 offset:1024
	ds_read_b128 v[176:179], v193 offset:2048
	ds_read_b128 v[194:197], v193 offset:3072
	s_add_u32 s0, s0, s8
	s_addc_u32 s1, s1, s9
	s_mov_b32 m0, s11
	v_lshl_add_u64 v[240:241], s[0:1], 0, v[136:137]
	ds_read_b128 v[202:205], v167 offset:32768
	ds_read_b128 v[206:209], v167 offset:33792
	ds_read_b128 v[210:213], v167 offset:34816
	ds_read_b128 v[214:217], v167 offset:35840
	ds_read_b128 v[218:221], v167 offset:36864
	ds_read_b128 v[222:225], v167 offset:37888
	ds_read_b128 v[226:229], v167 offset:38912
	ds_read_b128 v[230:233], v167 offset:39936
	global_load_lds_dwordx4 v[240:241], off
	v_lshl_add_u64 v[240:241], s[0:1], 0, v[138:139]
	s_mov_b32 m0, s13
	s_nop 0
	global_load_lds_dwordx4 v[240:241], off
	s_waitcnt vmcnt(8)
	s_waitcnt lgkmcnt(0)
	s_barrier
	s_waitcnt lgkmcnt(0)
	v_mfma_f32_16x16x32_bf16 v[124:127], v[128:131], v[202:205], v[124:127]
	v_mfma_f32_16x16x32_bf16 v[120:123], v[146:149], v[202:205], v[120:123]
	v_mfma_f32_16x16x32_bf16 v[108:111], v[128:131], v[210:213], v[108:111]
	v_mfma_f32_16x16x32_bf16 v[104:107], v[146:149], v[210:213], v[104:107]
	v_mfma_f32_16x16x32_bf16 v[92:95], v[128:131], v[218:221], v[92:95]
	v_mfma_f32_16x16x32_bf16 v[88:91], v[146:149], v[218:221], v[88:91]
	v_mfma_f32_16x16x32_bf16 v[76:79], v[128:131], v[226:229], v[76:79]
	v_mfma_f32_16x16x32_bf16 v[72:75], v[146:149], v[226:229], v[72:75]
	v_mfma_f32_16x16x32_bf16 v[124:127], v[132:135], v[206:209], v[124:127]
	v_mfma_f32_16x16x32_bf16 v[120:123], v[158:161], v[206:209], v[120:123]
	v_mfma_f32_16x16x32_bf16 v[108:111], v[132:135], v[214:217], v[108:111]
	v_mfma_f32_16x16x32_bf16 v[104:107], v[158:161], v[214:217], v[104:107]
	v_mfma_f32_16x16x32_bf16 v[92:95], v[132:135], v[222:225], v[92:95]
	v_mfma_f32_16x16x32_bf16 v[88:91], v[158:161], v[222:225], v[88:91]
	v_mfma_f32_16x16x32_bf16 v[76:79], v[132:135], v[230:233], v[76:79]
	v_mfma_f32_16x16x32_bf16 v[72:75], v[158:161], v[230:233], v[72:75]
	v_mfma_f32_16x16x32_bf16 v[116:119], v[168:171], v[202:205], v[116:119]
	v_mfma_f32_16x16x32_bf16 v[112:115], v[176:179], v[202:205], v[112:115]
	v_mfma_f32_16x16x32_bf16 v[100:103], v[168:171], v[210:213], v[100:103]
	v_mfma_f32_16x16x32_bf16 v[96:99], v[176:179], v[210:213], v[96:99]
	v_mfma_f32_16x16x32_bf16 v[84:87], v[168:171], v[218:221], v[84:87]
	v_mfma_f32_16x16x32_bf16 v[80:83], v[176:179], v[218:221], v[80:83]
	v_mfma_f32_16x16x32_bf16 v[68:71], v[168:171], v[226:229], v[68:71]
	v_mfma_f32_16x16x32_bf16 v[64:67], v[176:179], v[226:229], v[64:67]
	v_mfma_f32_16x16x32_bf16 v[116:119], v[172:175], v[206:209], v[116:119]
	v_mfma_f32_16x16x32_bf16 v[112:115], v[194:197], v[206:209], v[112:115]
	v_mfma_f32_16x16x32_bf16 v[100:103], v[172:175], v[214:217], v[100:103]
	v_mfma_f32_16x16x32_bf16 v[96:99], v[194:197], v[214:217], v[96:99]
	v_mfma_f32_16x16x32_bf16 v[84:87], v[172:175], v[222:225], v[84:87]
	v_mfma_f32_16x16x32_bf16 v[80:83], v[194:197], v[222:225], v[80:83]
	v_mfma_f32_16x16x32_bf16 v[68:71], v[172:175], v[230:233], v[68:71]
	v_mfma_f32_16x16x32_bf16 v[64:67], v[194:197], v[230:233], v[64:67]
	s_barrier
	s_add_i32 s0, s14, s2
	v_lshl_add_u64 v[150:151], v[150:151], 0, s[36:37]
	s_mov_b32 m0, s0
	ds_read_b128 v[202:205], v167 offset:49152
	ds_read_b128 v[206:209], v167 offset:50176
	ds_read_b128 v[210:213], v167 offset:51200
	ds_read_b128 v[214:217], v167 offset:52224
	ds_read_b128 v[218:221], v167 offset:53248
	ds_read_b128 v[222:225], v167 offset:54272
	ds_read_b128 v[226:229], v167 offset:55296
	ds_read_b128 v[230:233], v167 offset:56320
	global_load_lds_dwordx4 v[150:151], off
	v_lshl_add_u64 v[150:151], v[162:163], 0, s[36:37]
	s_add_i32 m0, s0, 0x2000
	s_add_i32 s0, s15, s2
	global_load_lds_dwordx4 v[150:151], off
	v_lshl_add_u64 v[150:151], v[180:181], 0, s[36:37]
	s_mov_b32 m0, s0
	s_nop 0
	global_load_lds_dwordx4 v[150:151], off
	v_lshl_add_u64 v[150:151], v[234:235], 0, s[36:37]
	s_add_i32 m0, s0, 0x2000
	s_nop 0
	global_load_lds_dwordx4 v[150:151], off
	v_lshl_add_u64 v[150:151], v[236:237], 0, s[36:37]
	s_mov_b32 m0, s18
	s_nop 0
	global_load_lds_dwordx4 v[150:151], off
	v_lshl_add_u64 v[150:151], v[238:239], 0, s[36:37]
	s_mov_b32 m0, s28
	s_nop 0
	global_load_lds_dwordx4 v[150:151], off
	s_waitcnt vmcnt(8)
	s_waitcnt lgkmcnt(0)
	s_barrier
	s_waitcnt lgkmcnt(0)
	v_mfma_f32_16x16x32_bf16 v[60:63], v[128:131], v[202:205], v[60:63]
	v_mfma_f32_16x16x32_bf16 v[56:59], v[146:149], v[202:205], v[56:59]
	v_mfma_f32_16x16x32_bf16 v[44:47], v[128:131], v[210:213], v[44:47]
	v_mfma_f32_16x16x32_bf16 v[40:43], v[146:149], v[210:213], v[40:43]
	v_mfma_f32_16x16x32_bf16 v[28:31], v[128:131], v[218:221], v[28:31]
	v_mfma_f32_16x16x32_bf16 v[24:27], v[146:149], v[218:221], v[24:27]
	v_mfma_f32_16x16x32_bf16 v[12:15], v[128:131], v[226:229], v[12:15]
	v_mfma_f32_16x16x32_bf16 v[8:11], v[146:149], v[226:229], v[8:11]
	v_mfma_f32_16x16x32_bf16 v[60:63], v[132:135], v[206:209], v[60:63]
	v_mfma_f32_16x16x32_bf16 v[56:59], v[158:161], v[206:209], v[56:59]
	v_mfma_f32_16x16x32_bf16 v[44:47], v[132:135], v[214:217], v[44:47]
	v_mfma_f32_16x16x32_bf16 v[40:43], v[158:161], v[214:217], v[40:43]
	v_mfma_f32_16x16x32_bf16 v[28:31], v[132:135], v[222:225], v[28:31]
	v_mfma_f32_16x16x32_bf16 v[24:27], v[158:161], v[222:225], v[24:27]
	v_mfma_f32_16x16x32_bf16 v[12:15], v[132:135], v[230:233], v[12:15]
	v_mfma_f32_16x16x32_bf16 v[8:11], v[158:161], v[230:233], v[8:11]
	v_mfma_f32_16x16x32_bf16 v[52:55], v[168:171], v[202:205], v[52:55]
	v_mfma_f32_16x16x32_bf16 v[48:51], v[176:179], v[202:205], v[48:51]
	v_mfma_f32_16x16x32_bf16 v[36:39], v[168:171], v[210:213], v[36:39]
	v_mfma_f32_16x16x32_bf16 v[32:35], v[176:179], v[210:213], v[32:35]
	v_mfma_f32_16x16x32_bf16 v[20:23], v[168:171], v[218:221], v[20:23]
	v_mfma_f32_16x16x32_bf16 v[16:19], v[176:179], v[218:221], v[16:19]
	v_mfma_f32_16x16x32_bf16 v[4:7], v[168:171], v[226:229], v[4:7]
	v_mfma_f32_16x16x32_bf16 v[0:3], v[176:179], v[226:229], v[0:3]
	v_mfma_f32_16x16x32_bf16 v[52:55], v[172:175], v[206:209], v[52:55]
	v_mfma_f32_16x16x32_bf16 v[48:51], v[194:197], v[206:209], v[48:51]
	v_mfma_f32_16x16x32_bf16 v[36:39], v[172:175], v[214:217], v[36:39]
	v_mfma_f32_16x16x32_bf16 v[32:35], v[194:197], v[214:217], v[32:35]
	v_mfma_f32_16x16x32_bf16 v[20:23], v[172:175], v[222:225], v[20:23]
	v_mfma_f32_16x16x32_bf16 v[16:19], v[194:197], v[222:225], v[16:19]
	v_mfma_f32_16x16x32_bf16 v[4:7], v[172:175], v[230:233], v[4:7]
	v_mfma_f32_16x16x32_bf16 v[0:3], v[194:197], v[230:233], v[0:3]
	s_barrier
	s_add_u32 s42, s42, 0x100
	s_addc_u32 s43, s43, 0
	s_add_u32 s44, s44, 0x100
	s_addc_u32 s45, s45, 0
	s_cmp_ge_u32 s47, s31
	s_mov_b32 s0, s47
.LBB0_482:
	s_add_i32 s47, s0, 2
	s_add_u32 s14, s42, 0x80
	s_addc_u32 s1, s43, 0
	s_add_i32 s15, 0, 0x10000
	s_cmp_eq_u32 s29, s0
	s_cselect_b32 s1, s77, s1
	s_cselect_b32 s0, s76, s14
	v_add_u32_e32 v150, s15, v165
	s_cselect_b32 s83, s79, s45
	s_cselect_b32 s82, s78, s44
	s_add_i32 s14, 0, 0x14000
	ds_read_b128 v[128:131], v150
	ds_read_b128 v[132:135], v150 offset:1024
	ds_read_b128 v[146:149], v150 offset:2048
	ds_read_b128 v[158:161], v150 offset:3072
	v_add_u32_e32 v150, s14, v165
	ds_read_b128 v[168:171], v150
	ds_read_b128 v[172:175], v150 offset:1024
	ds_read_b128 v[176:179], v150 offset:2048
	ds_read_b128 v[194:197], v150 offset:3072
	v_lshl_add_u64 v[150:151], s[42:43], 0, v[142:143]
	s_add_i32 m0, s3, 0xc000
	ds_read_b128 v[202:205], v167
	ds_read_b128 v[206:209], v167 offset:1024
	ds_read_b128 v[210:213], v167 offset:2048
	ds_read_b128 v[214:217], v167 offset:3072
	ds_read_b128 v[218:221], v167 offset:4096
	ds_read_b128 v[222:225], v167 offset:5120
	ds_read_b128 v[226:229], v167 offset:6144
	ds_read_b128 v[230:233], v167 offset:7168
	global_load_lds_dwordx4 v[150:151], off
	v_lshl_add_u64 v[150:151], s[42:43], 0, v[144:145]
	s_add_i32 m0, s3, 0xe000
	s_nop 0
	global_load_lds_dwordx4 v[150:151], off
	s_waitcnt vmcnt(8)
	s_waitcnt lgkmcnt(0)
	s_barrier
	s_waitcnt lgkmcnt(0)
	v_mfma_f32_16x16x32_bf16 v[124:127], v[128:131], v[202:205], v[124:127]
	v_mfma_f32_16x16x32_bf16 v[120:123], v[146:149], v[202:205], v[120:123]
	v_mfma_f32_16x16x32_bf16 v[108:111], v[128:131], v[210:213], v[108:111]
	v_mfma_f32_16x16x32_bf16 v[104:107], v[146:149], v[210:213], v[104:107]
	v_mfma_f32_16x16x32_bf16 v[92:95], v[128:131], v[218:221], v[92:95]
	v_mfma_f32_16x16x32_bf16 v[88:91], v[146:149], v[218:221], v[88:91]
	v_mfma_f32_16x16x32_bf16 v[76:79], v[128:131], v[226:229], v[76:79]
	v_mfma_f32_16x16x32_bf16 v[72:75], v[146:149], v[226:229], v[72:75]
	v_mfma_f32_16x16x32_bf16 v[124:127], v[132:135], v[206:209], v[124:127]
	v_mfma_f32_16x16x32_bf16 v[120:123], v[158:161], v[206:209], v[120:123]
	v_mfma_f32_16x16x32_bf16 v[108:111], v[132:135], v[214:217], v[108:111]
	v_mfma_f32_16x16x32_bf16 v[104:107], v[158:161], v[214:217], v[104:107]
	v_mfma_f32_16x16x32_bf16 v[92:95], v[132:135], v[222:225], v[92:95]
	v_mfma_f32_16x16x32_bf16 v[88:91], v[158:161], v[222:225], v[88:91]
	v_mfma_f32_16x16x32_bf16 v[76:79], v[132:135], v[230:233], v[76:79]
	v_mfma_f32_16x16x32_bf16 v[72:75], v[158:161], v[230:233], v[72:75]
	v_mfma_f32_16x16x32_bf16 v[116:119], v[168:171], v[202:205], v[116:119]
	v_mfma_f32_16x16x32_bf16 v[112:115], v[176:179], v[202:205], v[112:115]
	v_mfma_f32_16x16x32_bf16 v[100:103], v[168:171], v[210:213], v[100:103]
	v_mfma_f32_16x16x32_bf16 v[96:99], v[176:179], v[210:213], v[96:99]
	v_mfma_f32_16x16x32_bf16 v[84:87], v[168:171], v[218:221], v[84:87]
	v_mfma_f32_16x16x32_bf16 v[80:83], v[176:179], v[218:221], v[80:83]
	v_mfma_f32_16x16x32_bf16 v[68:71], v[168:171], v[226:229], v[68:71]
	v_mfma_f32_16x16x32_bf16 v[64:67], v[176:179], v[226:229], v[64:67]
	v_mfma_f32_16x16x32_bf16 v[116:119], v[172:175], v[206:209], v[116:119]
	v_mfma_f32_16x16x32_bf16 v[112:115], v[194:197], v[206:209], v[112:115]
	v_mfma_f32_16x16x32_bf16 v[100:103], v[172:175], v[214:217], v[100:103]
	v_mfma_f32_16x16x32_bf16 v[96:99], v[194:197], v[214:217], v[96:99]
	v_mfma_f32_16x16x32_bf16 v[84:87], v[172:175], v[222:225], v[84:87]
	v_mfma_f32_16x16x32_bf16 v[80:83], v[194:197], v[222:225], v[80:83]
	v_mfma_f32_16x16x32_bf16 v[68:71], v[172:175], v[230:233], v[68:71]
	v_mfma_f32_16x16x32_bf16 v[64:67], v[194:197], v[230:233], v[64:67]
	s_barrier
	s_add_i32 s15, s15, s2
	v_lshl_add_u64 v[150:151], s[82:83], 0, v[154:155]
	s_mov_b32 m0, s15
	ds_read_b128 v[202:205], v167 offset:16384
	ds_read_b128 v[206:209], v167 offset:17408
	ds_read_b128 v[210:213], v167 offset:18432
	ds_read_b128 v[214:217], v167 offset:19456
	ds_read_b128 v[218:221], v167 offset:20480
	ds_read_b128 v[222:225], v167 offset:21504
	ds_read_b128 v[226:229], v167 offset:22528
	ds_read_b128 v[230:233], v167 offset:23552
	global_load_lds_dwordx4 v[150:151], off
	s_add_i32 m0, s15, 0x2000
	v_lshl_add_u64 v[162:163], s[82:83], 0, v[140:141]
	s_add_u32 s82, s82, s24
	s_addc_u32 s83, s83, s25
	s_add_i32 s14, s14, s2
	global_load_lds_dwordx4 v[162:163], off
	v_lshl_add_u64 v[180:181], s[82:83], 0, v[154:155]
	s_mov_b32 m0, s14
	v_lshl_add_u64 v[234:235], s[82:83], 0, v[140:141]
	global_load_lds_dwordx4 v[180:181], off
	s_add_i32 m0, s14, 0x2000
	v_lshl_add_u64 v[236:237], s[0:1], 0, v[136:137]
	global_load_lds_dwordx4 v[234:235], off
	s_mov_b32 m0, s3
	v_lshl_add_u64 v[238:239], s[0:1], 0, v[138:139]
	global_load_lds_dwordx4 v[236:237], off
	s_mov_b32 m0, s10
	s_nop 0
	global_load_lds_dwordx4 v[238:239], off
	s_waitcnt vmcnt(8)
	s_waitcnt lgkmcnt(0)
	s_barrier
	s_waitcnt lgkmcnt(0)
	v_mfma_f32_16x16x32_bf16 v[60:63], v[128:131], v[202:205], v[60:63]
	v_mfma_f32_16x16x32_bf16 v[56:59], v[146:149], v[202:205], v[56:59]
	v_mfma_f32_16x16x32_bf16 v[44:47], v[128:131], v[210:213], v[44:47]
	v_mfma_f32_16x16x32_bf16 v[40:43], v[146:149], v[210:213], v[40:43]
	v_mfma_f32_16x16x32_bf16 v[28:31], v[128:131], v[218:221], v[28:31]
	v_mfma_f32_16x16x32_bf16 v[24:27], v[146:149], v[218:221], v[24:27]
	v_mfma_f32_16x16x32_bf16 v[12:15], v[128:131], v[226:229], v[12:15]
	v_mfma_f32_16x16x32_bf16 v[8:11], v[146:149], v[226:229], v[8:11]
	v_mfma_f32_16x16x32_bf16 v[60:63], v[132:135], v[206:209], v[60:63]
	v_mfma_f32_16x16x32_bf16 v[56:59], v[158:161], v[206:209], v[56:59]
	v_mfma_f32_16x16x32_bf16 v[44:47], v[132:135], v[214:217], v[44:47]
	v_mfma_f32_16x16x32_bf16 v[40:43], v[158:161], v[214:217], v[40:43]
	v_mfma_f32_16x16x32_bf16 v[28:31], v[132:135], v[222:225], v[28:31]
	v_mfma_f32_16x16x32_bf16 v[24:27], v[158:161], v[222:225], v[24:27]
	v_mfma_f32_16x16x32_bf16 v[12:15], v[132:135], v[230:233], v[12:15]
	v_mfma_f32_16x16x32_bf16 v[8:11], v[158:161], v[230:233], v[8:11]
	v_mfma_f32_16x16x32_bf16 v[52:55], v[168:171], v[202:205], v[52:55]
	v_mfma_f32_16x16x32_bf16 v[48:51], v[176:179], v[202:205], v[48:51]
	v_mfma_f32_16x16x32_bf16 v[36:39], v[168:171], v[210:213], v[36:39]
	v_mfma_f32_16x16x32_bf16 v[32:35], v[176:179], v[210:213], v[32:35]
	v_mfma_f32_16x16x32_bf16 v[20:23], v[168:171], v[218:221], v[20:23]
	v_mfma_f32_16x16x32_bf16 v[16:19], v[176:179], v[218:221], v[16:19]
	v_mfma_f32_16x16x32_bf16 v[4:7], v[168:171], v[226:229], v[4:7]
	v_mfma_f32_16x16x32_bf16 v[0:3], v[176:179], v[226:229], v[0:3]
	v_mfma_f32_16x16x32_bf16 v[52:55], v[172:175], v[206:209], v[52:55]
	v_mfma_f32_16x16x32_bf16 v[48:51], v[194:197], v[206:209], v[48:51]
	v_mfma_f32_16x16x32_bf16 v[36:39], v[172:175], v[214:217], v[36:39]
	v_mfma_f32_16x16x32_bf16 v[32:35], v[194:197], v[214:217], v[32:35]
	v_mfma_f32_16x16x32_bf16 v[20:23], v[172:175], v[222:225], v[20:23]
	v_mfma_f32_16x16x32_bf16 v[16:19], v[194:197], v[222:225], v[16:19]
	v_mfma_f32_16x16x32_bf16 v[4:7], v[172:175], v[230:233], v[4:7]
	v_mfma_f32_16x16x32_bf16 v[0:3], v[194:197], v[230:233], v[0:3]
	s_barrier
	s_add_i32 s14, 0, 0x18000
	s_add_i32 s15, 0, 0x1c000
	v_add_u32_e32 v158, s14, v165
	v_add_u32_e32 v193, s15, v165
	ds_read_b128 v[128:131], v158
	ds_read_b128 v[132:135], v158 offset:1024
	ds_read_b128 v[146:149], v158 offset:2048
	ds_read_b128 v[158:161], v158 offset:3072
	ds_read_b128 v[168:171], v193
	ds_read_b128 v[172:175], v193 offset:1024
	ds_read_b128 v[176:179], v193 offset:2048
	ds_read_b128 v[194:197], v193 offset:3072
	s_add_u32 s0, s0, s8
	s_addc_u32 s1, s1, s9
	s_mov_b32 m0, s11
	v_lshl_add_u64 v[240:241], s[0:1], 0, v[136:137]
	ds_read_b128 v[202:205], v167 offset:32768
	ds_read_b128 v[206:209], v167 offset:33792
	ds_read_b128 v[210:213], v167 offset:34816
	ds_read_b128 v[214:217], v167 offset:35840
	ds_read_b128 v[218:221], v167 offset:36864
	ds_read_b128 v[222:225], v167 offset:37888
	ds_read_b128 v[226:229], v167 offset:38912
	ds_read_b128 v[230:233], v167 offset:39936
	global_load_lds_dwordx4 v[240:241], off
	v_lshl_add_u64 v[240:241], s[0:1], 0, v[138:139]
	s_mov_b32 m0, s13
	s_nop 0
	global_load_lds_dwordx4 v[240:241], off
	s_waitcnt vmcnt(8)
	s_waitcnt lgkmcnt(0)
	s_barrier
	s_waitcnt lgkmcnt(0)
	v_mfma_f32_16x16x32_bf16 v[124:127], v[128:131], v[202:205], v[124:127]
	v_mfma_f32_16x16x32_bf16 v[120:123], v[146:149], v[202:205], v[120:123]
	v_mfma_f32_16x16x32_bf16 v[108:111], v[128:131], v[210:213], v[108:111]
	v_mfma_f32_16x16x32_bf16 v[104:107], v[146:149], v[210:213], v[104:107]
	v_mfma_f32_16x16x32_bf16 v[92:95], v[128:131], v[218:221], v[92:95]
	v_mfma_f32_16x16x32_bf16 v[88:91], v[146:149], v[218:221], v[88:91]
	v_mfma_f32_16x16x32_bf16 v[76:79], v[128:131], v[226:229], v[76:79]
	v_mfma_f32_16x16x32_bf16 v[72:75], v[146:149], v[226:229], v[72:75]
	v_mfma_f32_16x16x32_bf16 v[124:127], v[132:135], v[206:209], v[124:127]
	v_mfma_f32_16x16x32_bf16 v[120:123], v[158:161], v[206:209], v[120:123]
	v_mfma_f32_16x16x32_bf16 v[108:111], v[132:135], v[214:217], v[108:111]
	v_mfma_f32_16x16x32_bf16 v[104:107], v[158:161], v[214:217], v[104:107]
	v_mfma_f32_16x16x32_bf16 v[92:95], v[132:135], v[222:225], v[92:95]
	v_mfma_f32_16x16x32_bf16 v[88:91], v[158:161], v[222:225], v[88:91]
	v_mfma_f32_16x16x32_bf16 v[76:79], v[132:135], v[230:233], v[76:79]
	v_mfma_f32_16x16x32_bf16 v[72:75], v[158:161], v[230:233], v[72:75]
	v_mfma_f32_16x16x32_bf16 v[116:119], v[168:171], v[202:205], v[116:119]
	v_mfma_f32_16x16x32_bf16 v[112:115], v[176:179], v[202:205], v[112:115]
	v_mfma_f32_16x16x32_bf16 v[100:103], v[168:171], v[210:213], v[100:103]
	v_mfma_f32_16x16x32_bf16 v[96:99], v[176:179], v[210:213], v[96:99]
	v_mfma_f32_16x16x32_bf16 v[84:87], v[168:171], v[218:221], v[84:87]
	v_mfma_f32_16x16x32_bf16 v[80:83], v[176:179], v[218:221], v[80:83]
	v_mfma_f32_16x16x32_bf16 v[68:71], v[168:171], v[226:229], v[68:71]
	v_mfma_f32_16x16x32_bf16 v[64:67], v[176:179], v[226:229], v[64:67]
	v_mfma_f32_16x16x32_bf16 v[116:119], v[172:175], v[206:209], v[116:119]
	v_mfma_f32_16x16x32_bf16 v[112:115], v[194:197], v[206:209], v[112:115]
	v_mfma_f32_16x16x32_bf16 v[100:103], v[172:175], v[214:217], v[100:103]
	v_mfma_f32_16x16x32_bf16 v[96:99], v[194:197], v[214:217], v[96:99]
	v_mfma_f32_16x16x32_bf16 v[84:87], v[172:175], v[222:225], v[84:87]
	v_mfma_f32_16x16x32_bf16 v[80:83], v[194:197], v[222:225], v[80:83]
	v_mfma_f32_16x16x32_bf16 v[68:71], v[172:175], v[230:233], v[68:71]
	v_mfma_f32_16x16x32_bf16 v[64:67], v[194:197], v[230:233], v[64:67]
	s_barrier
	s_add_i32 s0, s14, s2
	v_lshl_add_u64 v[150:151], v[150:151], 0, s[36:37]
	s_mov_b32 m0, s0
	ds_read_b128 v[202:205], v167 offset:49152
	ds_read_b128 v[206:209], v167 offset:50176
	ds_read_b128 v[210:213], v167 offset:51200
	ds_read_b128 v[214:217], v167 offset:52224
	ds_read_b128 v[218:221], v167 offset:53248
	ds_read_b128 v[222:225], v167 offset:54272
	ds_read_b128 v[226:229], v167 offset:55296
	ds_read_b128 v[230:233], v167 offset:56320
	global_load_lds_dwordx4 v[150:151], off
	v_lshl_add_u64 v[150:151], v[162:163], 0, s[36:37]
	s_add_i32 m0, s0, 0x2000
	s_add_i32 s0, s15, s2
	global_load_lds_dwordx4 v[150:151], off
	v_lshl_add_u64 v[150:151], v[180:181], 0, s[36:37]
	s_mov_b32 m0, s0
	s_nop 0
	global_load_lds_dwordx4 v[150:151], off
	v_lshl_add_u64 v[150:151], v[234:235], 0, s[36:37]
	s_add_i32 m0, s0, 0x2000
	s_nop 0
	global_load_lds_dwordx4 v[150:151], off
	v_lshl_add_u64 v[150:151], v[236:237], 0, s[36:37]
	s_mov_b32 m0, s18
	s_nop 0
	global_load_lds_dwordx4 v[150:151], off
	v_lshl_add_u64 v[150:151], v[238:239], 0, s[36:37]
	s_mov_b32 m0, s28
	s_nop 0
	global_load_lds_dwordx4 v[150:151], off
	s_waitcnt vmcnt(8)
	s_waitcnt lgkmcnt(0)
	s_barrier
	s_waitcnt lgkmcnt(0)
	v_mfma_f32_16x16x32_bf16 v[60:63], v[128:131], v[202:205], v[60:63]
	v_mfma_f32_16x16x32_bf16 v[56:59], v[146:149], v[202:205], v[56:59]
	v_mfma_f32_16x16x32_bf16 v[44:47], v[128:131], v[210:213], v[44:47]
	v_mfma_f32_16x16x32_bf16 v[40:43], v[146:149], v[210:213], v[40:43]
	v_mfma_f32_16x16x32_bf16 v[28:31], v[128:131], v[218:221], v[28:31]
	v_mfma_f32_16x16x32_bf16 v[24:27], v[146:149], v[218:221], v[24:27]
	v_mfma_f32_16x16x32_bf16 v[12:15], v[128:131], v[226:229], v[12:15]
	v_mfma_f32_16x16x32_bf16 v[8:11], v[146:149], v[226:229], v[8:11]
	v_mfma_f32_16x16x32_bf16 v[60:63], v[132:135], v[206:209], v[60:63]
	v_mfma_f32_16x16x32_bf16 v[56:59], v[158:161], v[206:209], v[56:59]
	v_mfma_f32_16x16x32_bf16 v[44:47], v[132:135], v[214:217], v[44:47]
	v_mfma_f32_16x16x32_bf16 v[40:43], v[158:161], v[214:217], v[40:43]
	v_mfma_f32_16x16x32_bf16 v[28:31], v[132:135], v[222:225], v[28:31]
	v_mfma_f32_16x16x32_bf16 v[24:27], v[158:161], v[222:225], v[24:27]
	v_mfma_f32_16x16x32_bf16 v[12:15], v[132:135], v[230:233], v[12:15]
	v_mfma_f32_16x16x32_bf16 v[8:11], v[158:161], v[230:233], v[8:11]
	v_mfma_f32_16x16x32_bf16 v[52:55], v[168:171], v[202:205], v[52:55]
	v_mfma_f32_16x16x32_bf16 v[48:51], v[176:179], v[202:205], v[48:51]
	v_mfma_f32_16x16x32_bf16 v[36:39], v[168:171], v[210:213], v[36:39]
	v_mfma_f32_16x16x32_bf16 v[32:35], v[176:179], v[210:213], v[32:35]
	v_mfma_f32_16x16x32_bf16 v[20:23], v[168:171], v[218:221], v[20:23]
	v_mfma_f32_16x16x32_bf16 v[16:19], v[176:179], v[218:221], v[16:19]
	v_mfma_f32_16x16x32_bf16 v[4:7], v[168:171], v[226:229], v[4:7]
	v_mfma_f32_16x16x32_bf16 v[0:3], v[176:179], v[226:229], v[0:3]
	v_mfma_f32_16x16x32_bf16 v[52:55], v[172:175], v[206:209], v[52:55]
	v_mfma_f32_16x16x32_bf16 v[48:51], v[194:197], v[206:209], v[48:51]
	v_mfma_f32_16x16x32_bf16 v[36:39], v[172:175], v[214:217], v[36:39]
	v_mfma_f32_16x16x32_bf16 v[32:35], v[194:197], v[214:217], v[32:35]
	v_mfma_f32_16x16x32_bf16 v[20:23], v[172:175], v[222:225], v[20:23]
	v_mfma_f32_16x16x32_bf16 v[16:19], v[194:197], v[222:225], v[16:19]
	v_mfma_f32_16x16x32_bf16 v[4:7], v[172:175], v[230:233], v[4:7]
	v_mfma_f32_16x16x32_bf16 v[0:3], v[194:197], v[230:233], v[0:3]
	s_barrier
	s_add_u32 s42, s42, 0x100
	s_addc_u32 s43, s43, 0
	s_add_u32 s44, s44, 0x100
	s_addc_u32 s45, s45, 0
	s_cmp_ge_u32 s47, s31
	s_mov_b32 s0, s47
	s_cbranch_scc0 .LBB0_482
	s_and_b64 vcc, exec, s[66:67]
	s_cbranch_vccz .LBB0_485
	s_barrier
